# also: every read-once input load of P0 (f32 weights, x, mem) marked nt
# baseline (speedup 1.0000x reference)
.LBB0_9:
	s_cmpk_gt_i32 s52, 0xcff
	s_mov_b64 s[4:5], -1
	s_cbranch_scc0 .LBB0_87
	s_cmpk_gt_u32 s52, 0xeff
	s_cbranch_scc0 .LBB0_84
	s_cmpk_gt_u32 s52, 0x10ff
	s_cbranch_scc0 .LBB0_81
	s_cmpk_gt_u32 s52, 0x12ff
	s_cbranch_scc0 .LBB0_78
	s_cmpk_gt_u32 s52, 0x137f
	s_cbranch_scc0 .LBB0_59
	s_cmpk_gt_u32 s52, 0x13ff
	s_cbranch_scc0 .LBB0_56
	s_cmpk_gt_u32 s52, 0x1bff
	s_cbranch_scc0 .LBB0_37
	s_cmpk_gt_u32 s52, 0x23ff
	s_cbranch_scc0 .LBB0_34
	s_load_dwordx16 s[72:87], s[0:1], 0x80
	s_add_i32 s4, s52, 0xffffdc00
	s_lshr_b32 s16, s4, 8
	s_lshl_b64 s[4:5], s[16:17], 21
	v_ashrrev_i32_e32 v19, 3, v18
	s_waitcnt lgkmcnt(0)
	s_add_u32 s53, s76, s4
	s_addc_u32 s56, s77, s5
	s_lshl_b32 s4, s16, 10
	s_mov_b32 s5, s17
	s_lshl_b64 s[4:5], s[4:5], 2
	s_add_u32 s54, s72, s4
	s_addc_u32 s55, s73, s5
	s_and_b32 s20, s40, 0x1e0
	s_and_b32 s21, s44, 0x3c0
	v_lshlrev_b32_e32 v2, 2, v18
	s_lshl_b32 s4, s20, 2
	v_and_b32_e32 v20, 28, v2
	s_add_u32 s4, s53, s4
	v_add_u32_e32 v16, s21, v19
	s_addc_u32 s5, s56, 0
	v_lshlrev_b32_e32 v10, 2, v20
	v_ashrrev_i32_e32 v17, 31, v16
	v_lshl_add_u64 v[12:13], s[4:5], 0, v[10:11]
	v_lshlrev_b64 v[2:3], 11, v[16:17]
	v_lshl_add_u64 v[2:3], v[12:13], 0, v[2:3]
	global_load_dwordx4 v[6:9], v[2:3], off nt
	v_cmp_ne_u32_e64 s[4:5], 1, v1
	s_andn2_b64 vcc, exec, s[6:7]
	v_lshl_add_u64 v[14:15], v[16:17], 2, s[54:55]
	s_cbranch_vccnz .LBB0_19
	global_load_dword v2, v[14:15], off
	s_waitcnt vmcnt(0)
	v_pk_mul_f32 v[8:9], v[8:9], v[2:3] op_sel_hi:[1,0]
	v_pk_mul_f32 v[6:7], v[6:7], v[2:3] op_sel_hi:[1,0]
.LBB0_19:
	v_add_u32_e32 v17, 8, v19
	v_add_u32_e32 v2, s21, v17
	v_ashrrev_i32_e32 v3, 31, v2
	v_lshlrev_b64 v[2:3], 11, v[2:3]
	v_lshl_add_u64 v[2:3], v[12:13], 0, v[2:3]
	global_load_dwordx4 v[2:5], v[2:3], off nt
	v_readlane_b32 s53, v253, 35
	v_readlane_b32 s60, v253, 40
	s_and_b64 vcc, exec, s[4:5]
	v_lshl_add_u32 v10, v20, 2, s53
	v_mul_lo_u32 v20, v19, s50
	v_add_u32_e32 v10, v10, v20
	v_readlane_b32 s61, v253, 41
	s_waitcnt vmcnt(1)
	ds_write2_b32 v10, v6, v7 offset1:1
	ds_write2_b32 v10, v8, v9 offset0:2 offset1:3
	s_cbranch_vccnz .LBB0_21
	global_load_dword v6, v[14:15], off offset:32
	s_waitcnt vmcnt(0)
	v_pk_mul_f32 v[4:5], v[4:5], v[6:7] op_sel_hi:[1,0]
	v_pk_mul_f32 v[2:3], v[2:3], v[6:7] op_sel_hi:[1,0]
.LBB0_21:
	v_add_u32_e32 v20, 16, v19
	v_add_u32_e32 v6, s21, v20
	v_ashrrev_i32_e32 v7, 31, v6
	v_lshlrev_b64 v[6:7], 11, v[6:7]
	v_lshl_add_u64 v[6:7], v[12:13], 0, v[6:7]
	global_load_dwordx4 v[6:9], v[6:7], off nt
	v_add_u32_e32 v21, 0x420, v10
	s_waitcnt vmcnt(1)
	ds_write2_b32 v21, v2, v3 offset1:1
	v_add_u32_e32 v2, 0x428, v10
	s_and_b64 vcc, exec, s[4:5]
	ds_write2_b32 v2, v4, v5 offset1:1
	s_cbranch_vccnz .LBB0_23
	global_load_dword v2, v[14:15], off offset:64
	s_waitcnt vmcnt(0)
	v_pk_mul_f32 v[8:9], v[8:9], v[2:3] op_sel_hi:[1,0]
	v_pk_mul_f32 v[6:7], v[6:7], v[2:3] op_sel_hi:[1,0]
.LBB0_23:
	v_add_u32_e32 v21, 24, v19
	v_add_u32_e32 v2, s21, v21
	v_ashrrev_i32_e32 v3, 31, v2
	v_lshlrev_b64 v[2:3], 11, v[2:3]
	v_lshl_add_u64 v[2:3], v[12:13], 0, v[2:3]
	global_load_dwordx4 v[2:5], v[2:3], off nt
	v_add_u32_e32 v22, 0x840, v10
	s_waitcnt vmcnt(1)
	ds_write2_b32 v22, v6, v7 offset1:1
	v_add_u32_e32 v6, 0x848, v10
	s_and_b64 vcc, exec, s[4:5]
	ds_write2_b32 v6, v8, v9 offset1:1
	s_cbranch_vccnz .LBB0_25
	global_load_dword v6, v[14:15], off offset:96
	s_waitcnt vmcnt(0)
	v_pk_mul_f32 v[4:5], v[4:5], v[6:7] op_sel_hi:[1,0]
	v_pk_mul_f32 v[2:3], v[2:3], v[6:7] op_sel_hi:[1,0]
.LBB0_25:
	v_add_u32_e32 v6, 32, v16
	v_ashrrev_i32_e32 v7, 31, v6
	v_lshlrev_b64 v[6:7], 11, v[6:7]
	v_lshl_add_u64 v[6:7], v[12:13], 0, v[6:7]
	global_load_dwordx4 v[6:9], v[6:7], off nt
	v_add_u32_e32 v22, 0xc60, v10
	s_waitcnt vmcnt(1)
	ds_write2_b32 v22, v2, v3 offset1:1
	v_add_u32_e32 v2, 0xc68, v10
	s_and_b64 vcc, exec, s[4:5]
	ds_write2_b32 v2, v4, v5 offset1:1
	s_cbranch_vccnz .LBB0_27
	global_load_dword v2, v[14:15], off offset:128
	s_waitcnt vmcnt(0)
	v_pk_mul_f32 v[8:9], v[8:9], v[2:3] op_sel_hi:[1,0]
	v_pk_mul_f32 v[6:7], v[6:7], v[2:3] op_sel_hi:[1,0]
.LBB0_27:
	v_add_u32_e32 v2, 40, v16
	v_ashrrev_i32_e32 v3, 31, v2
	v_lshlrev_b64 v[2:3], 11, v[2:3]
	v_lshl_add_u64 v[2:3], v[12:13], 0, v[2:3]
	global_load_dwordx4 v[2:5], v[2:3], off nt
	v_add_u32_e32 v22, 0x1080, v10
	s_waitcnt vmcnt(1)
	ds_write2_b32 v22, v6, v7 offset1:1
	v_add_u32_e32 v6, 0x1088, v10
	s_and_b64 vcc, exec, s[4:5]
	ds_write2_b32 v6, v8, v9 offset1:1
	s_cbranch_vccnz .LBB0_29
	global_load_dword v6, v[14:15], off offset:160
	s_waitcnt vmcnt(0)
	v_pk_mul_f32 v[4:5], v[4:5], v[6:7] op_sel_hi:[1,0]
	v_pk_mul_f32 v[2:3], v[2:3], v[6:7] op_sel_hi:[1,0]
.LBB0_29:
	v_add_u32_e32 v6, 48, v16
	v_ashrrev_i32_e32 v7, 31, v6
	v_lshlrev_b64 v[6:7], 11, v[6:7]
	v_lshl_add_u64 v[6:7], v[12:13], 0, v[6:7]
	global_load_dwordx4 v[6:9], v[6:7], off nt
	v_add_u32_e32 v22, 0x14a0, v10
	s_waitcnt vmcnt(1)
	ds_write2_b32 v22, v2, v3 offset1:1
	v_add_u32_e32 v2, 0x14a8, v10
	s_and_b64 vcc, exec, s[4:5]
	ds_write2_b32 v2, v4, v5 offset1:1
	s_cbranch_vccnz .LBB0_31
	global_load_dword v2, v[14:15], off offset:192
	s_waitcnt vmcnt(0)
	v_pk_mul_f32 v[8:9], v[8:9], v[2:3] op_sel_hi:[1,0]
	v_pk_mul_f32 v[6:7], v[6:7], v[2:3] op_sel_hi:[1,0]
.LBB0_31:
	v_add_u32_e32 v2, 56, v16
	v_ashrrev_i32_e32 v3, 31, v2
	v_lshlrev_b64 v[2:3], 11, v[2:3]
	v_lshl_add_u64 v[2:3], v[12:13], 0, v[2:3]
	global_load_dwordx4 v[2:5], v[2:3], off nt
	v_add_u32_e32 v12, 0x18c0, v10
	s_waitcnt vmcnt(1)
	ds_write2_b32 v12, v6, v7 offset1:1
	v_add_u32_e32 v6, 0x18c8, v10
	s_and_b64 vcc, exec, s[4:5]
	ds_write2_b32 v6, v8, v9 offset1:1
	s_cbranch_vccnz .LBB0_33
	global_load_dword v6, v[14:15], off offset:224
	s_waitcnt vmcnt(0)
	v_pk_mul_f32 v[4:5], v[4:5], v[6:7] op_sel_hi:[1,0]
	v_pk_mul_f32 v[2:3], v[2:3], v[6:7] op_sel_hi:[1,0]

.LBB0_34:
	s_and_b64 vcc, exec, s[4:5]
	s_cbranch_vccz .LBB0_36
	s_load_dwordx16 s[72:87], s[0:1], 0x80
	s_and_b32 s5, s46, 0x1ffc0
	s_and_b32 s4, s40, 0x3e0
	v_ashrrev_i32_e32 v19, 3, v18
	s_lshl_b32 s16, s4, 2
	v_add_u32_e32 v36, s5, v19
	v_add_u32_e32 v40, 8, v19
	v_add_u32_e32 v41, 16, v19
	v_add_u32_e32 v42, 24, v19
	s_waitcnt lgkmcnt(0)
	s_add_u32 s20, s84, s16
	v_lshlrev_b32_e32 v2, 4, v18
	v_add_u32_e32 v4, s5, v40
	v_add_u32_e32 v12, s5, v41
	v_add_u32_e32 v14, s5, v42
	v_add_u32_e32 v24, 32, v36
	v_add_u32_e32 v26, 40, v36
	s_addc_u32 s21, s85, 0
	v_and_b32_e32 v10, 0x70, v2
	v_ashrrev_i32_e32 v37, 31, v36
	v_ashrrev_i32_e32 v5, 31, v4
	v_ashrrev_i32_e32 v13, 31, v12
	v_ashrrev_i32_e32 v15, 31, v14
	v_ashrrev_i32_e32 v25, 31, v24
	v_ashrrev_i32_e32 v27, 31, v26
	v_lshl_add_u64 v[16:17], s[20:21], 0, v[10:11]
	v_lshlrev_b64 v[2:3], 12, v[36:37]
	v_lshlrev_b64 v[4:5], 12, v[4:5]
	v_lshlrev_b64 v[12:13], 12, v[12:13]
	v_lshlrev_b64 v[14:15], 12, v[14:15]
	v_lshlrev_b64 v[24:25], 12, v[24:25]
	v_lshlrev_b64 v[26:27], 12, v[26:27]
	v_lshl_add_u64 v[2:3], v[16:17], 0, v[2:3]
	v_lshl_add_u64 v[6:7], v[16:17], 0, v[4:5]
	v_lshl_add_u64 v[12:13], v[16:17], 0, v[12:13]
	v_lshl_add_u64 v[20:21], v[16:17], 0, v[14:15]
	v_lshl_add_u64 v[24:25], v[16:17], 0, v[24:25]
	v_lshl_add_u64 v[28:29], v[16:17], 0, v[26:27]
	global_load_dwordx4 v[2:5], v[2:3], off nt
	s_nop 0
	global_load_dwordx4 v[6:9], v[6:7], off nt
	s_nop 0
	global_load_dwordx4 v[12:15], v[12:13], off nt
	s_nop 0
	global_load_dwordx4 v[20:23], v[20:21], off nt
	s_nop 0
	global_load_dwordx4 v[24:27], v[24:25], off nt
	s_nop 0
	global_load_dwordx4 v[28:31], v[28:29], off nt
	v_add_u32_e32 v32, 48, v36
	v_ashrrev_i32_e32 v33, 31, v32
	v_lshlrev_b64 v[32:33], 12, v[32:33]
	v_add_u32_e32 v36, 56, v36
	v_lshl_add_u64 v[32:33], v[16:17], 0, v[32:33]
	v_ashrrev_i32_e32 v37, 31, v36
	global_load_dwordx4 v[32:35], v[32:33], off nt
	v_lshlrev_b64 v[36:37], 12, v[36:37]
	v_lshl_add_u64 v[16:17], v[16:17], 0, v[36:37]
	global_load_dwordx4 v[36:39], v[16:17], off nt
	v_lshlrev_b32_e32 v16, 3, v18
	v_mul_lo_u32 v17, v19, s50
	v_readlane_b32 s16, v253, 35
	v_and_b32_e32 v16, 56, v16
	s_lshl_b32 s5, s5, 1
	v_add3_u32 v10, s16, v10, v17
	v_mul_u32_u24_e32 v17, 0x84, v16
	v_add_u32_e32 v43, 0x420, v10
	v_add_u32_e32 v44, 0x428, v10
	v_add_u32_e32 v45, 0x840, v10
	v_add_u32_e32 v46, 0x848, v10
	v_add_u32_e32 v47, 0xc60, v10
	v_add_u32_e32 v48, 0xc68, v10
	v_add_u32_e32 v49, 0x1080, v10
	v_add_u32_e32 v50, 0x1088, v10
	v_add_u32_e32 v51, 0x14a0, v10
	v_add_u32_e32 v52, 0x14a8, v10
	v_add_u32_e32 v53, 0x18c0, v10
	v_add_u32_e32 v54, 0x18c8, v10
	v_add_u32_e32 v55, 0x1ce0, v10
	v_add_u32_e32 v56, 0x1ce8, v10
	s_add_u32 s20, s3, s5
	s_addc_u32 s21, s22, 0
	v_readlane_b32 s60, v253, 40
	v_readlane_b32 s61, v253, 41
	s_waitcnt vmcnt(7)
	ds_write2_b32 v10, v2, v3 offset1:1
	ds_write2_b32 v10, v4, v5 offset0:2 offset1:3
	s_waitcnt vmcnt(6)
	ds_write2_b32 v43, v6, v7 offset1:1
	ds_write2_b32 v44, v8, v9 offset1:1
	s_waitcnt vmcnt(5)
	ds_write2_b32 v45, v12, v13 offset1:1
	ds_write2_b32 v46, v14, v15 offset1:1
	s_waitcnt vmcnt(4)
	ds_write2_b32 v47, v20, v21 offset1:1
	ds_write2_b32 v48, v22, v23 offset1:1
	s_waitcnt vmcnt(3)
	ds_write2_b32 v49, v24, v25 offset1:1
	ds_write2_b32 v50, v26, v27 offset1:1
	s_waitcnt vmcnt(2)
	ds_write2_b32 v51, v28, v29 offset1:1
	ds_write2_b32 v52, v30, v31 offset1:1
	s_waitcnt vmcnt(1)
	ds_write2_b32 v53, v32, v33 offset1:1
	ds_write2_b32 v54, v34, v35 offset1:1
	s_waitcnt vmcnt(0)
	ds_write2_b32 v55, v36, v37 offset1:1
	ds_write2_b32 v56, v38, v39 offset1:1
	v_lshlrev_b32_e32 v2, 2, v19
	s_waitcnt lgkmcnt(0)
	v_add3_u32 v30, s16, v17, v2
	v_lshlrev_b32_e32 v10, 1, v16
	ds_read2_b32 v[6:7], v30 offset0:33 offset1:41
	ds_read2_b32 v[8:9], v30 offset1:8
	ds_read2_b32 v[12:13], v30 offset0:66 offset1:74
	ds_read2_b32 v[14:15], v30 offset0:99 offset1:107
	ds_read2_b32 v[16:17], v30 offset0:132 offset1:140
	ds_read2_b32 v[20:21], v30 offset0:165 offset1:173
	ds_read2_b32 v[22:23], v30 offset0:198 offset1:206
	ds_read2_b32 v[24:25], v30 offset0:231 offset1:239
	v_add_u32_e32 v28, s4, v19
	v_ashrrev_i32_e32 v29, 31, v28
	v_lshl_add_u64 v[26:27], s[20:21], 0, v[10:11]
	v_lshlrev_b64 v[28:29], 13, v[28:29]
	s_waitcnt lgkmcnt(6)
	v_cvt_pk_bf16_f32 v2, v8, v6
	s_waitcnt lgkmcnt(4)
	v_cvt_pk_bf16_f32 v3, v12, v14
	s_waitcnt lgkmcnt(2)
	v_cvt_pk_bf16_f32 v4, v16, v20
	s_waitcnt lgkmcnt(0)
	v_cvt_pk_bf16_f32 v5, v22, v24
	v_lshl_add_u64 v[28:29], v[26:27], 0, v[28:29]
	v_add_u32_e32 v6, s4, v40
	global_store_dwordx4 v[28:29], v[2:5], off
	s_nop 1
	v_cvt_pk_bf16_f32 v2, v9, v7
	v_ashrrev_i32_e32 v7, 31, v6
	v_cvt_pk_bf16_f32 v3, v13, v15
	v_cvt_pk_bf16_f32 v4, v17, v21
	v_cvt_pk_bf16_f32 v5, v23, v25
	v_lshlrev_b64 v[6:7], 13, v[6:7]
	ds_read2_b32 v[8:9], v30 offset0:49 offset1:57
	ds_read2_b32 v[12:13], v30 offset0:16 offset1:24
	ds_read2_b32 v[14:15], v30 offset0:82 offset1:90
	ds_read2_b32 v[16:17], v30 offset0:115 offset1:123
	ds_read2_b32 v[20:21], v30 offset0:148 offset1:156
	ds_read2_b32 v[22:23], v30 offset0:181 offset1:189
	ds_read2_b32 v[24:25], v30 offset0:214 offset1:222
	ds_read2_b32 v[28:29], v30 offset0:247 offset1:255
	v_lshl_add_u64 v[6:7], v[26:27], 0, v[6:7]
	global_store_dwordx4 v[6:7], v[2:5], off
	v_add_u32_e32 v6, s4, v41
	v_ashrrev_i32_e32 v7, 31, v6
	v_lshlrev_b64 v[6:7], 13, v[6:7]
	s_waitcnt lgkmcnt(6)
	v_cvt_pk_bf16_f32 v2, v12, v8
	s_waitcnt lgkmcnt(4)
	v_cvt_pk_bf16_f32 v3, v14, v16
	s_waitcnt lgkmcnt(2)
	v_cvt_pk_bf16_f32 v4, v20, v22
	s_waitcnt lgkmcnt(0)
	v_cvt_pk_bf16_f32 v5, v24, v28
	v_lshl_add_u64 v[6:7], v[26:27], 0, v[6:7]
	global_store_dwordx4 v[6:7], v[2:5], off
	v_add_u32_e32 v6, s4, v42
	v_ashrrev_i32_e32 v7, 31, v6
	v_lshlrev_b64 v[6:7], 13, v[6:7]
	v_cvt_pk_bf16_f32 v2, v13, v9
	v_cvt_pk_bf16_f32 v3, v15, v17
	v_cvt_pk_bf16_f32 v4, v21, v23
	v_cvt_pk_bf16_f32 v5, v25, v29
	v_lshl_add_u64 v[6:7], v[26:27], 0, v[6:7]
	global_store_dwordx4 v[6:7], v[2:5], off
	s_waitcnt lgkmcnt(0)

.LBB0_37:
	s_andn2_b64 vcc, exec, s[4:5]
	s_cbranch_vccnz .LBB0_55
	s_load_dwordx16 s[72:87], s[0:1], 0x80
	s_add_i32 s4, s52, 0xec00
	s_lshr_b32 s4, s4, 1
	s_and_b32 s16, s40, 0xfe0
	s_and_b32 s20, s4, 0x7fc0
	v_ashrrev_i32_e32 v19, 3, v18
	v_lshlrev_b32_e32 v2, 2, v18
	s_lshl_b32 s4, s16, 2
	v_and_b32_e32 v20, 28, v2
	s_waitcnt lgkmcnt(0)
	s_add_u32 s4, s82, s4
	v_add_u32_e32 v16, s20, v19
	s_addc_u32 s5, s83, 0
	v_lshlrev_b32_e32 v10, 2, v20
	v_ashrrev_i32_e32 v17, 31, v16
	v_lshl_add_u64 v[12:13], s[4:5], 0, v[10:11]
	v_lshlrev_b64 v[2:3], 14, v[16:17]
	v_lshl_add_u64 v[2:3], v[12:13], 0, v[2:3]
	global_load_dwordx4 v[2:5], v[2:3], off nt
	v_cndmask_b32_e64 v6, 0, 1, s[10:11]
	v_cmp_ne_u32_e64 s[4:5], 1, v6
	s_andn2_b64 vcc, exec, s[10:11]
	v_lshl_add_u64 v[14:15], v[16:17], 2, s[80:81]
	s_cbranch_vccnz .LBB0_40
	global_load_dword v6, v[14:15], off
	s_waitcnt vmcnt(0)
	v_pk_mul_f32 v[4:5], v[4:5], v[6:7] op_sel_hi:[1,0]
	v_pk_mul_f32 v[2:3], v[2:3], v[6:7] op_sel_hi:[1,0]
.LBB0_40:
	v_add_u32_e32 v17, 8, v19
	v_add_u32_e32 v6, s20, v17
	v_ashrrev_i32_e32 v7, 31, v6
	v_lshlrev_b64 v[6:7], 14, v[6:7]
	v_lshl_add_u64 v[6:7], v[12:13], 0, v[6:7]
	global_load_dwordx4 v[6:9], v[6:7], off nt
	v_readlane_b32 s21, v253, 35
	v_readlane_b32 s60, v253, 40
	s_and_b64 vcc, exec, s[4:5]
	v_lshl_add_u32 v10, v20, 2, s21
	v_mul_lo_u32 v20, v19, s50
	v_add_u32_e32 v10, v10, v20
	v_readlane_b32 s61, v253, 41
	s_waitcnt vmcnt(1)
	ds_write2_b32 v10, v2, v3 offset1:1
	ds_write2_b32 v10, v4, v5 offset0:2 offset1:3
	s_cbranch_vccnz .LBB0_42
	global_load_dword v2, v[14:15], off offset:32
	s_waitcnt vmcnt(0)
	v_pk_mul_f32 v[8:9], v[8:9], v[2:3] op_sel_hi:[1,0]
	v_pk_mul_f32 v[6:7], v[6:7], v[2:3] op_sel_hi:[1,0]
.LBB0_42:
	v_add_u32_e32 v20, 16, v19
	v_add_u32_e32 v2, s20, v20
	v_ashrrev_i32_e32 v3, 31, v2
	v_lshlrev_b64 v[2:3], 14, v[2:3]
	v_lshl_add_u64 v[2:3], v[12:13], 0, v[2:3]
	global_load_dwordx4 v[2:5], v[2:3], off nt
	v_add_u32_e32 v21, 0x420, v10
	s_waitcnt vmcnt(1)
	ds_write2_b32 v21, v6, v7 offset1:1
	v_add_u32_e32 v6, 0x428, v10
	s_and_b64 vcc, exec, s[4:5]
	ds_write2_b32 v6, v8, v9 offset1:1
	s_cbranch_vccnz .LBB0_44
	global_load_dword v6, v[14:15], off offset:64
	s_waitcnt vmcnt(0)
	v_pk_mul_f32 v[4:5], v[4:5], v[6:7] op_sel_hi:[1,0]
	v_pk_mul_f32 v[2:3], v[2:3], v[6:7] op_sel_hi:[1,0]
.LBB0_44:
	v_add_u32_e32 v21, 24, v19
	v_add_u32_e32 v6, s20, v21
	v_ashrrev_i32_e32 v7, 31, v6
	v_lshlrev_b64 v[6:7], 14, v[6:7]
	v_lshl_add_u64 v[6:7], v[12:13], 0, v[6:7]
	global_load_dwordx4 v[6:9], v[6:7], off nt
	v_add_u32_e32 v22, 0x840, v10
	s_waitcnt vmcnt(1)
	ds_write2_b32 v22, v2, v3 offset1:1
	v_add_u32_e32 v2, 0x848, v10
	s_and_b64 vcc, exec, s[4:5]
	ds_write2_b32 v2, v4, v5 offset1:1
	s_cbranch_vccnz .LBB0_46
	global_load_dword v2, v[14:15], off offset:96
	s_waitcnt vmcnt(0)
	v_pk_mul_f32 v[8:9], v[8:9], v[2:3] op_sel_hi:[1,0]
	v_pk_mul_f32 v[6:7], v[6:7], v[2:3] op_sel_hi:[1,0]
.LBB0_46:
	v_add_u32_e32 v2, 32, v16
	v_ashrrev_i32_e32 v3, 31, v2
	v_lshlrev_b64 v[2:3], 14, v[2:3]
	v_lshl_add_u64 v[2:3], v[12:13], 0, v[2:3]
	global_load_dwordx4 v[2:5], v[2:3], off nt
	v_add_u32_e32 v22, 0xc60, v10
	s_waitcnt vmcnt(1)
	ds_write2_b32 v22, v6, v7 offset1:1
	v_add_u32_e32 v6, 0xc68, v10
	s_and_b64 vcc, exec, s[4:5]
	ds_write2_b32 v6, v8, v9 offset1:1
	s_cbranch_vccnz .LBB0_48
	global_load_dword v6, v[14:15], off offset:128
	s_waitcnt vmcnt(0)
	v_pk_mul_f32 v[4:5], v[4:5], v[6:7] op_sel_hi:[1,0]
	v_pk_mul_f32 v[2:3], v[2:3], v[6:7] op_sel_hi:[1,0]
.LBB0_48:
	v_add_u32_e32 v6, 40, v16
	v_ashrrev_i32_e32 v7, 31, v6
	v_lshlrev_b64 v[6:7], 14, v[6:7]
	v_lshl_add_u64 v[6:7], v[12:13], 0, v[6:7]
	global_load_dwordx4 v[6:9], v[6:7], off nt
	v_add_u32_e32 v22, 0x1080, v10
	s_waitcnt vmcnt(1)
	ds_write2_b32 v22, v2, v3 offset1:1
	v_add_u32_e32 v2, 0x1088, v10
	s_and_b64 vcc, exec, s[4:5]
	ds_write2_b32 v2, v4, v5 offset1:1
	s_cbranch_vccnz .LBB0_50
	global_load_dword v2, v[14:15], off offset:160
	s_waitcnt vmcnt(0)
	v_pk_mul_f32 v[8:9], v[8:9], v[2:3] op_sel_hi:[1,0]
	v_pk_mul_f32 v[6:7], v[6:7], v[2:3] op_sel_hi:[1,0]
.LBB0_50:
	v_add_u32_e32 v2, 48, v16
	v_ashrrev_i32_e32 v3, 31, v2
	v_lshlrev_b64 v[2:3], 14, v[2:3]
	v_lshl_add_u64 v[2:3], v[12:13], 0, v[2:3]
	global_load_dwordx4 v[2:5], v[2:3], off nt
	v_add_u32_e32 v22, 0x14a0, v10
	s_waitcnt vmcnt(1)
	ds_write2_b32 v22, v6, v7 offset1:1
	v_add_u32_e32 v6, 0x14a8, v10
	s_and_b64 vcc, exec, s[4:5]
	ds_write2_b32 v6, v8, v9 offset1:1
	s_cbranch_vccnz .LBB0_52
	global_load_dword v6, v[14:15], off offset:192
	s_waitcnt vmcnt(0)
	v_pk_mul_f32 v[4:5], v[4:5], v[6:7] op_sel_hi:[1,0]
	v_pk_mul_f32 v[2:3], v[2:3], v[6:7] op_sel_hi:[1,0]
.LBB0_52:
	v_add_u32_e32 v6, 56, v16
	v_ashrrev_i32_e32 v7, 31, v6
	v_lshlrev_b64 v[6:7], 14, v[6:7]
	v_lshl_add_u64 v[6:7], v[12:13], 0, v[6:7]
	global_load_dwordx4 v[6:9], v[6:7], off nt
	v_add_u32_e32 v12, 0x18c0, v10
	s_waitcnt vmcnt(1)
	ds_write2_b32 v12, v2, v3 offset1:1
	v_add_u32_e32 v2, 0x18c8, v10
	s_and_b64 vcc, exec, s[4:5]
	ds_write2_b32 v2, v4, v5 offset1:1
	s_cbranch_vccnz .LBB0_54
	global_load_dword v2, v[14:15], off offset:224
	s_waitcnt vmcnt(0)
	v_pk_mul_f32 v[8:9], v[8:9], v[2:3] op_sel_hi:[1,0]
	v_pk_mul_f32 v[6:7], v[6:7], v[2:3] op_sel_hi:[1,0]

.LBB0_56:
	s_andn2_b64 vcc, exec, s[4:5]
	s_cbranch_vccnz .LBB0_58
	s_load_dwordx16 s[72:87], s[0:1], 0x80
	s_add_i32 s4, s46, 0xfffe3800
	s_and_b32 s4, s4, 0x1c0
	s_xor_b32 s5, s4, 0x100
	s_and_b32 s4, s40, 0x3e0
	v_ashrrev_i32_e32 v19, 3, v18
	s_lshl_b32 s16, s4, 2
	v_add_u32_e32 v36, s5, v19
	v_add_u32_e32 v40, 8, v19
	v_add_u32_e32 v41, 16, v19
	v_add_u32_e32 v42, 24, v19
	s_waitcnt lgkmcnt(0)
	s_add_u32 s20, s78, s16
	v_lshlrev_b32_e32 v2, 4, v18
	v_add_u32_e32 v4, s5, v40
	v_add_u32_e32 v12, s5, v41
	v_add_u32_e32 v14, s5, v42
	v_add_u32_e32 v24, 32, v36
	v_add_u32_e32 v26, 40, v36
	s_addc_u32 s21, s79, 0
	v_and_b32_e32 v10, 0x70, v2
	v_ashrrev_i32_e32 v37, 31, v36
	v_ashrrev_i32_e32 v5, 31, v4
	v_ashrrev_i32_e32 v13, 31, v12
	v_ashrrev_i32_e32 v15, 31, v14
	v_ashrrev_i32_e32 v25, 31, v24
	v_ashrrev_i32_e32 v27, 31, v26
	v_lshl_add_u64 v[16:17], s[20:21], 0, v[10:11]
	v_lshlrev_b64 v[2:3], 12, v[36:37]
	v_lshlrev_b64 v[4:5], 12, v[4:5]
	v_lshlrev_b64 v[12:13], 12, v[12:13]
	v_lshlrev_b64 v[14:15], 12, v[14:15]
	v_lshlrev_b64 v[24:25], 12, v[24:25]
	v_lshlrev_b64 v[26:27], 12, v[26:27]
	v_lshl_add_u64 v[2:3], v[16:17], 0, v[2:3]
	v_lshl_add_u64 v[6:7], v[16:17], 0, v[4:5]
	v_lshl_add_u64 v[12:13], v[16:17], 0, v[12:13]
	v_lshl_add_u64 v[20:21], v[16:17], 0, v[14:15]
	v_lshl_add_u64 v[24:25], v[16:17], 0, v[24:25]
	v_lshl_add_u64 v[28:29], v[16:17], 0, v[26:27]
	global_load_dwordx4 v[2:5], v[2:3], off nt
	s_nop 0
	global_load_dwordx4 v[6:9], v[6:7], off nt
	s_nop 0
	global_load_dwordx4 v[12:15], v[12:13], off nt
	s_nop 0
	global_load_dwordx4 v[20:23], v[20:21], off nt
	s_nop 0
	global_load_dwordx4 v[24:27], v[24:25], off nt
	s_nop 0
	global_load_dwordx4 v[28:31], v[28:29], off nt
	v_add_u32_e32 v32, 48, v36
	v_ashrrev_i32_e32 v33, 31, v32
	v_lshlrev_b64 v[32:33], 12, v[32:33]
	v_add_u32_e32 v36, 56, v36
	v_lshl_add_u64 v[32:33], v[16:17], 0, v[32:33]
	v_ashrrev_i32_e32 v37, 31, v36
	global_load_dwordx4 v[32:35], v[32:33], off nt
	v_lshlrev_b64 v[36:37], 12, v[36:37]
	v_lshl_add_u64 v[16:17], v[16:17], 0, v[36:37]
	global_load_dwordx4 v[36:39], v[16:17], off nt
	v_lshlrev_b32_e32 v16, 3, v18
	v_mul_lo_u32 v17, v19, s50
	v_readlane_b32 s16, v253, 35
	v_and_b32_e32 v16, 56, v16
	s_lshl_b32 s5, s5, 1
	v_add3_u32 v10, s16, v10, v17
	v_mul_u32_u24_e32 v17, 0x84, v16
	v_add_u32_e32 v43, 0x420, v10
	v_add_u32_e32 v44, 0x428, v10
	v_add_u32_e32 v45, 0x840, v10
	v_add_u32_e32 v46, 0x848, v10
	v_add_u32_e32 v47, 0xc60, v10
	v_add_u32_e32 v48, 0xc68, v10
	v_add_u32_e32 v49, 0x1080, v10
	v_add_u32_e32 v50, 0x1088, v10
	v_add_u32_e32 v51, 0x14a0, v10
	v_add_u32_e32 v52, 0x14a8, v10
	v_add_u32_e32 v53, 0x18c0, v10
	v_add_u32_e32 v54, 0x18c8, v10
	v_add_u32_e32 v55, 0x1ce0, v10
	v_add_u32_e32 v56, 0x1ce8, v10
	s_add_u32 s20, s25, s5
	s_addc_u32 s21, s26, 0
	v_readlane_b32 s60, v253, 40
	v_readlane_b32 s61, v253, 41
	s_waitcnt vmcnt(7)
	ds_write2_b32 v10, v2, v3 offset1:1
	ds_write2_b32 v10, v4, v5 offset0:2 offset1:3
	s_waitcnt vmcnt(6)
	ds_write2_b32 v43, v6, v7 offset1:1
	ds_write2_b32 v44, v8, v9 offset1:1
	s_waitcnt vmcnt(5)
	ds_write2_b32 v45, v12, v13 offset1:1
	ds_write2_b32 v46, v14, v15 offset1:1
	s_waitcnt vmcnt(4)
	ds_write2_b32 v47, v20, v21 offset1:1
	ds_write2_b32 v48, v22, v23 offset1:1
	s_waitcnt vmcnt(3)
	ds_write2_b32 v49, v24, v25 offset1:1
	ds_write2_b32 v50, v26, v27 offset1:1
	s_waitcnt vmcnt(2)
	ds_write2_b32 v51, v28, v29 offset1:1
	ds_write2_b32 v52, v30, v31 offset1:1
	s_waitcnt vmcnt(1)
	ds_write2_b32 v53, v32, v33 offset1:1
	ds_write2_b32 v54, v34, v35 offset1:1
	s_waitcnt vmcnt(0)
	ds_write2_b32 v55, v36, v37 offset1:1
	ds_write2_b32 v56, v38, v39 offset1:1
	v_lshlrev_b32_e32 v2, 2, v19
	s_waitcnt lgkmcnt(0)
	v_add3_u32 v30, s16, v17, v2
	v_lshlrev_b32_e32 v10, 1, v16
	ds_read2_b32 v[6:7], v30 offset0:33 offset1:41
	ds_read2_b32 v[8:9], v30 offset1:8
	ds_read2_b32 v[12:13], v30 offset0:66 offset1:74
	ds_read2_b32 v[14:15], v30 offset0:99 offset1:107
	ds_read2_b32 v[16:17], v30 offset0:132 offset1:140
	ds_read2_b32 v[20:21], v30 offset0:165 offset1:173
	ds_read2_b32 v[22:23], v30 offset0:198 offset1:206
	ds_read2_b32 v[24:25], v30 offset0:231 offset1:239
	v_add_u32_e32 v28, s4, v19
	v_ashrrev_i32_e32 v29, 31, v28
	v_lshl_add_u64 v[26:27], s[20:21], 0, v[10:11]
	v_lshlrev_b64 v[28:29], 9, v[28:29]
	s_waitcnt lgkmcnt(6)
	v_cvt_pk_bf16_f32 v2, v8, v6
	s_waitcnt lgkmcnt(4)
	v_cvt_pk_bf16_f32 v3, v12, v14
	s_waitcnt lgkmcnt(2)
	v_cvt_pk_bf16_f32 v4, v16, v20
	s_waitcnt lgkmcnt(0)
	v_cvt_pk_bf16_f32 v5, v22, v24
	v_lshl_add_u64 v[28:29], v[26:27], 0, v[28:29]
	v_add_u32_e32 v6, s4, v40
	global_store_dwordx4 v[28:29], v[2:5], off
	s_nop 1
	v_cvt_pk_bf16_f32 v2, v9, v7
	v_ashrrev_i32_e32 v7, 31, v6
	v_cvt_pk_bf16_f32 v3, v13, v15
	v_cvt_pk_bf16_f32 v4, v17, v21
	v_cvt_pk_bf16_f32 v5, v23, v25
	v_lshlrev_b64 v[6:7], 9, v[6:7]
	ds_read2_b32 v[8:9], v30 offset0:49 offset1:57
	ds_read2_b32 v[12:13], v30 offset0:16 offset1:24
	ds_read2_b32 v[14:15], v30 offset0:82 offset1:90
	ds_read2_b32 v[16:17], v30 offset0:115 offset1:123
	ds_read2_b32 v[20:21], v30 offset0:148 offset1:156
	ds_read2_b32 v[22:23], v30 offset0:181 offset1:189
	ds_read2_b32 v[24:25], v30 offset0:214 offset1:222
	ds_read2_b32 v[28:29], v30 offset0:247 offset1:255
	v_lshl_add_u64 v[6:7], v[26:27], 0, v[6:7]
	global_store_dwordx4 v[6:7], v[2:5], off
	v_add_u32_e32 v6, s4, v41
	v_ashrrev_i32_e32 v7, 31, v6
	v_lshlrev_b64 v[6:7], 9, v[6:7]
	s_waitcnt lgkmcnt(6)
	v_cvt_pk_bf16_f32 v2, v12, v8
	s_waitcnt lgkmcnt(4)
	v_cvt_pk_bf16_f32 v3, v14, v16
	s_waitcnt lgkmcnt(2)
	v_cvt_pk_bf16_f32 v4, v20, v22
	s_waitcnt lgkmcnt(0)
	v_cvt_pk_bf16_f32 v5, v24, v28
	v_lshl_add_u64 v[6:7], v[26:27], 0, v[6:7]
	global_store_dwordx4 v[6:7], v[2:5], off
	v_add_u32_e32 v6, s4, v42
	v_ashrrev_i32_e32 v7, 31, v6
	v_lshlrev_b64 v[6:7], 9, v[6:7]
	v_cvt_pk_bf16_f32 v2, v13, v9
	v_cvt_pk_bf16_f32 v3, v15, v17
	v_cvt_pk_bf16_f32 v4, v21, v23
	v_cvt_pk_bf16_f32 v5, v25, v29
	v_lshl_add_u64 v[6:7], v[26:27], 0, v[6:7]
	global_store_dwordx4 v[6:7], v[2:5], off
	s_waitcnt lgkmcnt(0)

.LBB0_59:
	s_andn2_b64 vcc, exec, s[4:5]
	s_cbranch_vccnz .LBB0_77
	s_load_dwordx16 s[72:87], s[0:1], 0x80
	s_and_b32 s16, s40, 0xe0
	s_and_b32 s20, s48, 0x7c0
	v_ashrrev_i32_e32 v19, 3, v18
	v_lshlrev_b32_e32 v2, 2, v18
	s_lshl_b32 s4, s16, 2
	v_and_b32_e32 v20, 28, v2
	s_waitcnt lgkmcnt(0)
	s_add_u32 s4, s74, s4
	v_add_u32_e32 v16, s20, v19
	s_addc_u32 s5, s75, 0
	v_lshlrev_b32_e32 v10, 2, v20
	v_ashrrev_i32_e32 v17, 31, v16
	v_lshl_add_u64 v[12:13], s[4:5], 0, v[10:11]
	v_lshlrev_b64 v[2:3], 10, v[16:17]
	v_lshl_add_u64 v[2:3], v[12:13], 0, v[2:3]
	global_load_dwordx4 v[2:5], v[2:3], off nt
	s_load_dwordx16 s[72:87], s[0:1], 0x40
	v_cndmask_b32_e64 v6, 0, 1, s[12:13]
	v_cmp_ne_u32_e64 s[4:5], 1, v6
	s_andn2_b64 vcc, exec, s[12:13]
	s_waitcnt lgkmcnt(0)
	v_lshl_add_u64 v[14:15], v[16:17], 2, s[86:87]
	s_cbranch_vccnz .LBB0_62
	global_load_dword v6, v[14:15], off
	s_waitcnt vmcnt(0)
	v_pk_mul_f32 v[4:5], v[4:5], v[6:7] op_sel_hi:[1,0]
	v_pk_mul_f32 v[2:3], v[2:3], v[6:7] op_sel_hi:[1,0]
.LBB0_62:
	v_add_u32_e32 v17, 8, v19
	v_add_u32_e32 v6, s20, v17
	v_ashrrev_i32_e32 v7, 31, v6
	v_lshlrev_b64 v[6:7], 10, v[6:7]
	v_lshl_add_u64 v[6:7], v[12:13], 0, v[6:7]
	global_load_dwordx4 v[6:9], v[6:7], off nt
	v_readlane_b32 s21, v253, 35
	v_readlane_b32 s60, v253, 40
	s_and_b64 vcc, exec, s[4:5]
	v_lshl_add_u32 v10, v20, 2, s21
	v_mul_lo_u32 v20, v19, s50
	v_add_u32_e32 v10, v10, v20
	v_readlane_b32 s61, v253, 41
	s_waitcnt vmcnt(1)
	ds_write2_b32 v10, v2, v3 offset1:1
	ds_write2_b32 v10, v4, v5 offset0:2 offset1:3
	s_cbranch_vccnz .LBB0_64
	global_load_dword v2, v[14:15], off offset:32
	s_waitcnt vmcnt(0)
	v_pk_mul_f32 v[8:9], v[8:9], v[2:3] op_sel_hi:[1,0]
	v_pk_mul_f32 v[6:7], v[6:7], v[2:3] op_sel_hi:[1,0]
.LBB0_64:
	v_add_u32_e32 v20, 16, v19
	v_add_u32_e32 v2, s20, v20
	v_ashrrev_i32_e32 v3, 31, v2
	v_lshlrev_b64 v[2:3], 10, v[2:3]
	v_lshl_add_u64 v[2:3], v[12:13], 0, v[2:3]
	global_load_dwordx4 v[2:5], v[2:3], off nt
	v_add_u32_e32 v21, 0x420, v10
	s_waitcnt vmcnt(1)
	ds_write2_b32 v21, v6, v7 offset1:1
	v_add_u32_e32 v6, 0x428, v10
	s_and_b64 vcc, exec, s[4:5]
	ds_write2_b32 v6, v8, v9 offset1:1
	s_cbranch_vccnz .LBB0_66
	global_load_dword v6, v[14:15], off offset:64
	s_waitcnt vmcnt(0)
	v_pk_mul_f32 v[4:5], v[4:5], v[6:7] op_sel_hi:[1,0]
	v_pk_mul_f32 v[2:3], v[2:3], v[6:7] op_sel_hi:[1,0]
.LBB0_66:
	v_add_u32_e32 v21, 24, v19
	v_add_u32_e32 v6, s20, v21
	v_ashrrev_i32_e32 v7, 31, v6
	v_lshlrev_b64 v[6:7], 10, v[6:7]
	v_lshl_add_u64 v[6:7], v[12:13], 0, v[6:7]
	global_load_dwordx4 v[6:9], v[6:7], off nt
	v_add_u32_e32 v22, 0x840, v10
	s_waitcnt vmcnt(1)
	ds_write2_b32 v22, v2, v3 offset1:1
	v_add_u32_e32 v2, 0x848, v10
	s_and_b64 vcc, exec, s[4:5]
	ds_write2_b32 v2, v4, v5 offset1:1
	s_cbranch_vccnz .LBB0_68
	global_load_dword v2, v[14:15], off offset:96
	s_waitcnt vmcnt(0)
	v_pk_mul_f32 v[8:9], v[8:9], v[2:3] op_sel_hi:[1,0]
	v_pk_mul_f32 v[6:7], v[6:7], v[2:3] op_sel_hi:[1,0]
.LBB0_68:
	v_add_u32_e32 v2, 32, v16
	v_ashrrev_i32_e32 v3, 31, v2
	v_lshlrev_b64 v[2:3], 10, v[2:3]
	v_lshl_add_u64 v[2:3], v[12:13], 0, v[2:3]
	global_load_dwordx4 v[2:5], v[2:3], off nt
	v_add_u32_e32 v22, 0xc60, v10
	s_waitcnt vmcnt(1)
	ds_write2_b32 v22, v6, v7 offset1:1
	v_add_u32_e32 v6, 0xc68, v10
	s_and_b64 vcc, exec, s[4:5]
	ds_write2_b32 v6, v8, v9 offset1:1
	s_cbranch_vccnz .LBB0_70
	global_load_dword v6, v[14:15], off offset:128
	s_waitcnt vmcnt(0)
	v_pk_mul_f32 v[4:5], v[4:5], v[6:7] op_sel_hi:[1,0]
	v_pk_mul_f32 v[2:3], v[2:3], v[6:7] op_sel_hi:[1,0]
.LBB0_70:
	v_add_u32_e32 v6, 40, v16
	v_ashrrev_i32_e32 v7, 31, v6
	v_lshlrev_b64 v[6:7], 10, v[6:7]
	v_lshl_add_u64 v[6:7], v[12:13], 0, v[6:7]
	global_load_dwordx4 v[6:9], v[6:7], off nt
	v_add_u32_e32 v22, 0x1080, v10
	s_waitcnt vmcnt(1)
	ds_write2_b32 v22, v2, v3 offset1:1
	v_add_u32_e32 v2, 0x1088, v10
	s_and_b64 vcc, exec, s[4:5]
	ds_write2_b32 v2, v4, v5 offset1:1
	s_cbranch_vccnz .LBB0_72
	global_load_dword v2, v[14:15], off offset:160
	s_waitcnt vmcnt(0)
	v_pk_mul_f32 v[8:9], v[8:9], v[2:3] op_sel_hi:[1,0]
	v_pk_mul_f32 v[6:7], v[6:7], v[2:3] op_sel_hi:[1,0]
.LBB0_72:
	v_add_u32_e32 v2, 48, v16
	v_ashrrev_i32_e32 v3, 31, v2
	v_lshlrev_b64 v[2:3], 10, v[2:3]
	v_lshl_add_u64 v[2:3], v[12:13], 0, v[2:3]
	global_load_dwordx4 v[2:5], v[2:3], off nt
	v_add_u32_e32 v22, 0x14a0, v10
	s_waitcnt vmcnt(1)
	ds_write2_b32 v22, v6, v7 offset1:1
	v_add_u32_e32 v6, 0x14a8, v10
	s_and_b64 vcc, exec, s[4:5]
	ds_write2_b32 v6, v8, v9 offset1:1
	s_cbranch_vccnz .LBB0_74
	global_load_dword v6, v[14:15], off offset:192
	s_waitcnt vmcnt(0)
	v_pk_mul_f32 v[4:5], v[4:5], v[6:7] op_sel_hi:[1,0]
	v_pk_mul_f32 v[2:3], v[2:3], v[6:7] op_sel_hi:[1,0]
.LBB0_74:
	v_add_u32_e32 v6, 56, v16
	v_ashrrev_i32_e32 v7, 31, v6
	v_lshlrev_b64 v[6:7], 10, v[6:7]
	v_lshl_add_u64 v[6:7], v[12:13], 0, v[6:7]
	global_load_dwordx4 v[6:9], v[6:7], off nt
	v_add_u32_e32 v12, 0x18c0, v10
	s_waitcnt vmcnt(1)
	ds_write2_b32 v12, v2, v3 offset1:1
	v_add_u32_e32 v2, 0x18c8, v10
	s_and_b64 vcc, exec, s[4:5]
	ds_write2_b32 v2, v4, v5 offset1:1
	s_cbranch_vccnz .LBB0_76
	global_load_dword v2, v[14:15], off offset:224
	s_waitcnt vmcnt(0)
	v_pk_mul_f32 v[8:9], v[8:9], v[2:3] op_sel_hi:[1,0]
	v_pk_mul_f32 v[6:7], v[6:7], v[2:3] op_sel_hi:[1,0]

.LBB0_78:
	s_andn2_b64 vcc, exec, s[4:5]
	s_cbranch_vccnz .LBB0_80
	s_load_dwordx16 s[72:87], s[0:1], 0x40
	s_add_i32 s4, s46, 0x1600
	s_and_b32 s5, s4, 0x1ffc0
	s_and_b32 s4, s40, 0x3e0
	v_ashrrev_i32_e32 v19, 3, v18
	s_lshl_b32 s16, s4, 2
	v_add_u32_e32 v36, s5, v19
	v_add_u32_e32 v40, 8, v19
	v_add_u32_e32 v41, 16, v19
	v_add_u32_e32 v42, 24, v19
	s_waitcnt lgkmcnt(0)
	s_add_u32 s20, s84, s16
	v_lshlrev_b32_e32 v2, 4, v18
	v_add_u32_e32 v4, s5, v40
	v_add_u32_e32 v12, s5, v41
	v_add_u32_e32 v14, s5, v42
	v_add_u32_e32 v24, 32, v36
	v_add_u32_e32 v26, 40, v36
	s_addc_u32 s21, s85, 0
	v_and_b32_e32 v10, 0x70, v2
	v_ashrrev_i32_e32 v37, 31, v36
	v_ashrrev_i32_e32 v5, 31, v4
	v_ashrrev_i32_e32 v13, 31, v12
	v_ashrrev_i32_e32 v15, 31, v14
	v_ashrrev_i32_e32 v25, 31, v24
	v_ashrrev_i32_e32 v27, 31, v26
	v_lshl_add_u64 v[16:17], s[20:21], 0, v[10:11]
	v_lshlrev_b64 v[2:3], 12, v[36:37]
	v_lshlrev_b64 v[4:5], 12, v[4:5]
	v_lshlrev_b64 v[12:13], 12, v[12:13]
	v_lshlrev_b64 v[14:15], 12, v[14:15]
	v_lshlrev_b64 v[24:25], 12, v[24:25]
	v_lshlrev_b64 v[26:27], 12, v[26:27]
	v_lshl_add_u64 v[2:3], v[16:17], 0, v[2:3]
	v_lshl_add_u64 v[6:7], v[16:17], 0, v[4:5]
	v_lshl_add_u64 v[12:13], v[16:17], 0, v[12:13]
	v_lshl_add_u64 v[20:21], v[16:17], 0, v[14:15]
	v_lshl_add_u64 v[24:25], v[16:17], 0, v[24:25]
	v_lshl_add_u64 v[28:29], v[16:17], 0, v[26:27]
	global_load_dwordx4 v[2:5], v[2:3], off nt
	s_nop 0
	global_load_dwordx4 v[6:9], v[6:7], off nt
	s_nop 0
	global_load_dwordx4 v[12:15], v[12:13], off nt
	s_nop 0
	global_load_dwordx4 v[20:23], v[20:21], off nt
	s_nop 0
	global_load_dwordx4 v[24:27], v[24:25], off nt
	s_nop 0
	global_load_dwordx4 v[28:31], v[28:29], off nt
	v_add_u32_e32 v32, 48, v36
	v_ashrrev_i32_e32 v33, 31, v32
	v_lshlrev_b64 v[32:33], 12, v[32:33]
	v_add_u32_e32 v36, 56, v36
	v_lshl_add_u64 v[32:33], v[16:17], 0, v[32:33]
	v_ashrrev_i32_e32 v37, 31, v36
	global_load_dwordx4 v[32:35], v[32:33], off nt
	v_lshlrev_b64 v[36:37], 12, v[36:37]
	v_lshl_add_u64 v[16:17], v[16:17], 0, v[36:37]
	global_load_dwordx4 v[36:39], v[16:17], off nt
	v_lshlrev_b32_e32 v16, 3, v18
	v_mul_lo_u32 v17, v19, s50
	v_readlane_b32 s16, v253, 35
	v_and_b32_e32 v16, 56, v16
	s_lshl_b32 s5, s5, 1
	v_add3_u32 v10, s16, v10, v17
	v_mul_u32_u24_e32 v17, 0x84, v16
	v_add_u32_e32 v43, 0x420, v10
	v_add_u32_e32 v44, 0x428, v10
	v_add_u32_e32 v45, 0x840, v10
	v_add_u32_e32 v46, 0x848, v10
	v_add_u32_e32 v47, 0xc60, v10
	v_add_u32_e32 v48, 0xc68, v10
	v_add_u32_e32 v49, 0x1080, v10
	v_add_u32_e32 v50, 0x1088, v10
	v_add_u32_e32 v51, 0x14a0, v10
	v_add_u32_e32 v52, 0x14a8, v10
	v_add_u32_e32 v53, 0x18c0, v10
	v_add_u32_e32 v54, 0x18c8, v10
	v_add_u32_e32 v55, 0x1ce0, v10
	v_add_u32_e32 v56, 0x1ce8, v10
	s_add_u32 s20, s29, s5
	s_addc_u32 s21, s30, 0
	v_readlane_b32 s60, v253, 40
	v_readlane_b32 s61, v253, 41
	s_waitcnt vmcnt(7)
	ds_write2_b32 v10, v2, v3 offset1:1
	ds_write2_b32 v10, v4, v5 offset0:2 offset1:3
	s_waitcnt vmcnt(6)
	ds_write2_b32 v43, v6, v7 offset1:1
	ds_write2_b32 v44, v8, v9 offset1:1
	s_waitcnt vmcnt(5)
	ds_write2_b32 v45, v12, v13 offset1:1
	ds_write2_b32 v46, v14, v15 offset1:1
	s_waitcnt vmcnt(4)
	ds_write2_b32 v47, v20, v21 offset1:1
	ds_write2_b32 v48, v22, v23 offset1:1
	s_waitcnt vmcnt(3)
	ds_write2_b32 v49, v24, v25 offset1:1
	ds_write2_b32 v50, v26, v27 offset1:1
	s_waitcnt vmcnt(2)
	ds_write2_b32 v51, v28, v29 offset1:1
	ds_write2_b32 v52, v30, v31 offset1:1
	s_waitcnt vmcnt(1)
	ds_write2_b32 v53, v32, v33 offset1:1
	ds_write2_b32 v54, v34, v35 offset1:1
	s_waitcnt vmcnt(0)
	ds_write2_b32 v55, v36, v37 offset1:1
	ds_write2_b32 v56, v38, v39 offset1:1
	v_lshlrev_b32_e32 v2, 2, v19
	s_waitcnt lgkmcnt(0)
	v_add3_u32 v30, s16, v17, v2
	v_lshlrev_b32_e32 v10, 1, v16
	ds_read2_b32 v[6:7], v30 offset0:33 offset1:41
	ds_read2_b32 v[8:9], v30 offset1:8
	ds_read2_b32 v[12:13], v30 offset0:66 offset1:74
	ds_read2_b32 v[14:15], v30 offset0:99 offset1:107
	ds_read2_b32 v[16:17], v30 offset0:132 offset1:140
	ds_read2_b32 v[20:21], v30 offset0:165 offset1:173
	ds_read2_b32 v[22:23], v30 offset0:198 offset1:206
	ds_read2_b32 v[24:25], v30 offset0:231 offset1:239
	v_add_u32_e32 v28, s4, v19
	v_ashrrev_i32_e32 v29, 31, v28
	v_lshl_add_u64 v[26:27], s[20:21], 0, v[10:11]
	v_lshlrev_b64 v[28:29], 11, v[28:29]
	s_waitcnt lgkmcnt(6)
	v_cvt_pk_bf16_f32 v2, v8, v6
	s_waitcnt lgkmcnt(4)
	v_cvt_pk_bf16_f32 v3, v12, v14
	s_waitcnt lgkmcnt(2)
	v_cvt_pk_bf16_f32 v4, v16, v20
	s_waitcnt lgkmcnt(0)
	v_cvt_pk_bf16_f32 v5, v22, v24
	v_lshl_add_u64 v[28:29], v[26:27], 0, v[28:29]
	v_add_u32_e32 v6, s4, v40
	global_store_dwordx4 v[28:29], v[2:5], off
	s_nop 1
	v_cvt_pk_bf16_f32 v2, v9, v7
	v_ashrrev_i32_e32 v7, 31, v6
	v_cvt_pk_bf16_f32 v3, v13, v15
	v_cvt_pk_bf16_f32 v4, v17, v21
	v_cvt_pk_bf16_f32 v5, v23, v25
	v_lshlrev_b64 v[6:7], 11, v[6:7]
	ds_read2_b32 v[8:9], v30 offset0:49 offset1:57
	ds_read2_b32 v[12:13], v30 offset0:16 offset1:24
	ds_read2_b32 v[14:15], v30 offset0:82 offset1:90
	ds_read2_b32 v[16:17], v30 offset0:115 offset1:123
	ds_read2_b32 v[20:21], v30 offset0:148 offset1:156
	ds_read2_b32 v[22:23], v30 offset0:181 offset1:189
	ds_read2_b32 v[24:25], v30 offset0:214 offset1:222
	ds_read2_b32 v[28:29], v30 offset0:247 offset1:255
	v_lshl_add_u64 v[6:7], v[26:27], 0, v[6:7]
	global_store_dwordx4 v[6:7], v[2:5], off
	v_add_u32_e32 v6, s4, v41
	v_ashrrev_i32_e32 v7, 31, v6
	v_lshlrev_b64 v[6:7], 11, v[6:7]
	s_waitcnt lgkmcnt(6)
	v_cvt_pk_bf16_f32 v2, v12, v8
	s_waitcnt lgkmcnt(4)
	v_cvt_pk_bf16_f32 v3, v14, v16
	s_waitcnt lgkmcnt(2)
	v_cvt_pk_bf16_f32 v4, v20, v22
	s_waitcnt lgkmcnt(0)
	v_cvt_pk_bf16_f32 v5, v24, v28
	v_lshl_add_u64 v[6:7], v[26:27], 0, v[6:7]
	global_store_dwordx4 v[6:7], v[2:5], off
	v_add_u32_e32 v6, s4, v42
	v_ashrrev_i32_e32 v7, 31, v6
	v_lshlrev_b64 v[6:7], 11, v[6:7]
	v_cvt_pk_bf16_f32 v2, v13, v9
	v_cvt_pk_bf16_f32 v3, v15, v17
	v_cvt_pk_bf16_f32 v4, v21, v23
	v_cvt_pk_bf16_f32 v5, v25, v29
	v_lshl_add_u64 v[6:7], v[26:27], 0, v[6:7]
	global_store_dwordx4 v[6:7], v[2:5], off
	s_waitcnt lgkmcnt(0)

.LBB0_81:
	s_andn2_b64 vcc, exec, s[4:5]
	s_cbranch_vccnz .LBB0_83
	s_load_dwordx16 s[72:87], s[0:1], 0x40
	s_add_i32 s4, s46, 0x1a00
	s_and_b32 s5, s4, 0x1ffc0
	s_and_b32 s4, s40, 0x3e0
	v_ashrrev_i32_e32 v19, 3, v18
	s_lshl_b32 s16, s4, 2
	v_add_u32_e32 v36, s5, v19
	v_add_u32_e32 v40, 8, v19
	v_add_u32_e32 v41, 16, v19
	v_add_u32_e32 v42, 24, v19
	s_waitcnt lgkmcnt(0)
	s_add_u32 s20, s82, s16
	v_lshlrev_b32_e32 v2, 4, v18
	v_add_u32_e32 v4, s5, v40
	v_add_u32_e32 v12, s5, v41
	v_add_u32_e32 v14, s5, v42
	v_add_u32_e32 v24, 32, v36
	v_add_u32_e32 v26, 40, v36
	s_addc_u32 s21, s83, 0
	v_and_b32_e32 v10, 0x70, v2
	v_ashrrev_i32_e32 v37, 31, v36
	v_ashrrev_i32_e32 v5, 31, v4
	v_ashrrev_i32_e32 v13, 31, v12
	v_ashrrev_i32_e32 v15, 31, v14
	v_ashrrev_i32_e32 v25, 31, v24
	v_ashrrev_i32_e32 v27, 31, v26
	v_lshl_add_u64 v[16:17], s[20:21], 0, v[10:11]
	v_lshlrev_b64 v[2:3], 12, v[36:37]
	v_lshlrev_b64 v[4:5], 12, v[4:5]
	v_lshlrev_b64 v[12:13], 12, v[12:13]
	v_lshlrev_b64 v[14:15], 12, v[14:15]
	v_lshlrev_b64 v[24:25], 12, v[24:25]
	v_lshlrev_b64 v[26:27], 12, v[26:27]
	v_lshl_add_u64 v[2:3], v[16:17], 0, v[2:3]
	v_lshl_add_u64 v[6:7], v[16:17], 0, v[4:5]
	v_lshl_add_u64 v[12:13], v[16:17], 0, v[12:13]
	v_lshl_add_u64 v[20:21], v[16:17], 0, v[14:15]
	v_lshl_add_u64 v[24:25], v[16:17], 0, v[24:25]
	v_lshl_add_u64 v[28:29], v[16:17], 0, v[26:27]
	global_load_dwordx4 v[2:5], v[2:3], off nt
	s_nop 0
	global_load_dwordx4 v[6:9], v[6:7], off nt
	s_nop 0
	global_load_dwordx4 v[12:15], v[12:13], off nt
	s_nop 0
	global_load_dwordx4 v[20:23], v[20:21], off nt
	s_nop 0
	global_load_dwordx4 v[24:27], v[24:25], off nt
	s_nop 0
	global_load_dwordx4 v[28:31], v[28:29], off nt
	v_add_u32_e32 v32, 48, v36
	v_ashrrev_i32_e32 v33, 31, v32
	v_lshlrev_b64 v[32:33], 12, v[32:33]
	v_add_u32_e32 v36, 56, v36
	v_lshl_add_u64 v[32:33], v[16:17], 0, v[32:33]
	v_ashrrev_i32_e32 v37, 31, v36
	global_load_dwordx4 v[32:35], v[32:33], off nt
	v_lshlrev_b64 v[36:37], 12, v[36:37]
	v_lshl_add_u64 v[16:17], v[16:17], 0, v[36:37]
	global_load_dwordx4 v[36:39], v[16:17], off nt
	v_lshlrev_b32_e32 v16, 3, v18
	v_mul_lo_u32 v17, v19, s50
	v_readlane_b32 s16, v253, 35
	v_and_b32_e32 v16, 56, v16
	s_lshl_b32 s5, s5, 1
	v_add3_u32 v10, s16, v10, v17
	v_mul_u32_u24_e32 v17, 0x84, v16
	v_add_u32_e32 v43, 0x420, v10
	v_add_u32_e32 v44, 0x428, v10
	v_add_u32_e32 v45, 0x840, v10
	v_add_u32_e32 v46, 0x848, v10
	v_add_u32_e32 v47, 0xc60, v10
	v_add_u32_e32 v48, 0xc68, v10
	v_add_u32_e32 v49, 0x1080, v10
	v_add_u32_e32 v50, 0x1088, v10
	v_add_u32_e32 v51, 0x14a0, v10
	v_add_u32_e32 v52, 0x14a8, v10
	v_add_u32_e32 v53, 0x18c0, v10
	v_add_u32_e32 v54, 0x18c8, v10
	v_add_u32_e32 v55, 0x1ce0, v10
	v_add_u32_e32 v56, 0x1ce8, v10
	s_add_u32 s20, s31, s5
	s_addc_u32 s21, s33, 0
	v_readlane_b32 s60, v253, 40
	v_readlane_b32 s61, v253, 41
	s_waitcnt vmcnt(7)
	ds_write2_b32 v10, v2, v3 offset1:1
	ds_write2_b32 v10, v4, v5 offset0:2 offset1:3
	s_waitcnt vmcnt(6)
	ds_write2_b32 v43, v6, v7 offset1:1
	ds_write2_b32 v44, v8, v9 offset1:1
	s_waitcnt vmcnt(5)
	ds_write2_b32 v45, v12, v13 offset1:1
	ds_write2_b32 v46, v14, v15 offset1:1
	s_waitcnt vmcnt(4)
	ds_write2_b32 v47, v20, v21 offset1:1
	ds_write2_b32 v48, v22, v23 offset1:1
	s_waitcnt vmcnt(3)
	ds_write2_b32 v49, v24, v25 offset1:1
	ds_write2_b32 v50, v26, v27 offset1:1
	s_waitcnt vmcnt(2)
	ds_write2_b32 v51, v28, v29 offset1:1
	ds_write2_b32 v52, v30, v31 offset1:1
	s_waitcnt vmcnt(1)
	ds_write2_b32 v53, v32, v33 offset1:1
	ds_write2_b32 v54, v34, v35 offset1:1
	s_waitcnt vmcnt(0)
	ds_write2_b32 v55, v36, v37 offset1:1
	ds_write2_b32 v56, v38, v39 offset1:1
	v_lshlrev_b32_e32 v2, 2, v19
	s_waitcnt lgkmcnt(0)
	v_add3_u32 v30, s16, v17, v2
	v_lshlrev_b32_e32 v10, 1, v16
	ds_read2_b32 v[6:7], v30 offset0:33 offset1:41
	ds_read2_b32 v[8:9], v30 offset1:8
	ds_read2_b32 v[12:13], v30 offset0:66 offset1:74
	ds_read2_b32 v[14:15], v30 offset0:99 offset1:107
	ds_read2_b32 v[16:17], v30 offset0:132 offset1:140
	ds_read2_b32 v[20:21], v30 offset0:165 offset1:173
	ds_read2_b32 v[22:23], v30 offset0:198 offset1:206
	ds_read2_b32 v[24:25], v30 offset0:231 offset1:239
	v_add_u32_e32 v28, s4, v19
	v_ashrrev_i32_e32 v29, 31, v28
	v_lshl_add_u64 v[26:27], s[20:21], 0, v[10:11]
	v_lshlrev_b64 v[28:29], 11, v[28:29]
	s_waitcnt lgkmcnt(6)
	v_cvt_pk_bf16_f32 v2, v8, v6
	s_waitcnt lgkmcnt(4)
	v_cvt_pk_bf16_f32 v3, v12, v14
	s_waitcnt lgkmcnt(2)
	v_cvt_pk_bf16_f32 v4, v16, v20
	s_waitcnt lgkmcnt(0)
	v_cvt_pk_bf16_f32 v5, v22, v24
	v_lshl_add_u64 v[28:29], v[26:27], 0, v[28:29]
	v_add_u32_e32 v6, s4, v40
	global_store_dwordx4 v[28:29], v[2:5], off
	s_nop 1
	v_cvt_pk_bf16_f32 v2, v9, v7
	v_ashrrev_i32_e32 v7, 31, v6
	v_cvt_pk_bf16_f32 v3, v13, v15
	v_cvt_pk_bf16_f32 v4, v17, v21
	v_cvt_pk_bf16_f32 v5, v23, v25
	v_lshlrev_b64 v[6:7], 11, v[6:7]
	ds_read2_b32 v[8:9], v30 offset0:49 offset1:57
	ds_read2_b32 v[12:13], v30 offset0:16 offset1:24
	ds_read2_b32 v[14:15], v30 offset0:82 offset1:90
	ds_read2_b32 v[16:17], v30 offset0:115 offset1:123
	ds_read2_b32 v[20:21], v30 offset0:148 offset1:156
	ds_read2_b32 v[22:23], v30 offset0:181 offset1:189
	ds_read2_b32 v[24:25], v30 offset0:214 offset1:222
	ds_read2_b32 v[28:29], v30 offset0:247 offset1:255
	v_lshl_add_u64 v[6:7], v[26:27], 0, v[6:7]
	global_store_dwordx4 v[6:7], v[2:5], off
	v_add_u32_e32 v6, s4, v41
	v_ashrrev_i32_e32 v7, 31, v6
	v_lshlrev_b64 v[6:7], 11, v[6:7]
	s_waitcnt lgkmcnt(6)
	v_cvt_pk_bf16_f32 v2, v12, v8
	s_waitcnt lgkmcnt(4)
	v_cvt_pk_bf16_f32 v3, v14, v16
	s_waitcnt lgkmcnt(2)
	v_cvt_pk_bf16_f32 v4, v20, v22
	s_waitcnt lgkmcnt(0)
	v_cvt_pk_bf16_f32 v5, v24, v28
	v_lshl_add_u64 v[6:7], v[26:27], 0, v[6:7]
	global_store_dwordx4 v[6:7], v[2:5], off
	v_add_u32_e32 v6, s4, v42
	v_ashrrev_i32_e32 v7, 31, v6
	v_lshlrev_b64 v[6:7], 11, v[6:7]
	v_cvt_pk_bf16_f32 v2, v13, v9
	v_cvt_pk_bf16_f32 v3, v15, v17
	v_cvt_pk_bf16_f32 v4, v21, v23
	v_cvt_pk_bf16_f32 v5, v25, v29
	v_lshl_add_u64 v[6:7], v[26:27], 0, v[6:7]
	global_store_dwordx4 v[6:7], v[2:5], off
	s_waitcnt lgkmcnt(0)

.LBB0_84:
	s_andn2_b64 vcc, exec, s[4:5]
	s_cbranch_vccnz .LBB0_86
	s_load_dwordx16 s[72:87], s[0:1], 0x40
	s_add_i32 s4, s46, 0x1e00
	s_and_b32 s5, s4, 0x1ffc0
	s_and_b32 s4, s40, 0x3e0
	v_ashrrev_i32_e32 v19, 3, v18
	s_lshl_b32 s16, s4, 2
	v_add_u32_e32 v36, s5, v19
	v_add_u32_e32 v40, 8, v19
	v_add_u32_e32 v41, 16, v19
	v_add_u32_e32 v42, 24, v19
	s_waitcnt lgkmcnt(0)
	s_add_u32 s20, s80, s16
	v_lshlrev_b32_e32 v2, 4, v18
	v_add_u32_e32 v4, s5, v40
	v_add_u32_e32 v12, s5, v41
	v_add_u32_e32 v14, s5, v42
	v_add_u32_e32 v24, 32, v36
	v_add_u32_e32 v26, 40, v36
	s_addc_u32 s21, s81, 0
	v_and_b32_e32 v10, 0x70, v2
	v_ashrrev_i32_e32 v37, 31, v36
	v_ashrrev_i32_e32 v5, 31, v4
	v_ashrrev_i32_e32 v13, 31, v12
	v_ashrrev_i32_e32 v15, 31, v14
	v_ashrrev_i32_e32 v25, 31, v24
	v_ashrrev_i32_e32 v27, 31, v26
	v_lshl_add_u64 v[16:17], s[20:21], 0, v[10:11]
	v_lshlrev_b64 v[2:3], 12, v[36:37]
	v_lshlrev_b64 v[4:5], 12, v[4:5]
	v_lshlrev_b64 v[12:13], 12, v[12:13]
	v_lshlrev_b64 v[14:15], 12, v[14:15]
	v_lshlrev_b64 v[24:25], 12, v[24:25]
	v_lshlrev_b64 v[26:27], 12, v[26:27]
	v_lshl_add_u64 v[2:3], v[16:17], 0, v[2:3]
	v_lshl_add_u64 v[6:7], v[16:17], 0, v[4:5]
	v_lshl_add_u64 v[12:13], v[16:17], 0, v[12:13]
	v_lshl_add_u64 v[20:21], v[16:17], 0, v[14:15]
	v_lshl_add_u64 v[24:25], v[16:17], 0, v[24:25]
	v_lshl_add_u64 v[28:29], v[16:17], 0, v[26:27]
	global_load_dwordx4 v[2:5], v[2:3], off nt
	s_nop 0
	global_load_dwordx4 v[6:9], v[6:7], off nt
	s_nop 0
	global_load_dwordx4 v[12:15], v[12:13], off nt
	s_nop 0
	global_load_dwordx4 v[20:23], v[20:21], off nt
	s_nop 0
	global_load_dwordx4 v[24:27], v[24:25], off nt
	s_nop 0
	global_load_dwordx4 v[28:31], v[28:29], off nt
	v_add_u32_e32 v32, 48, v36
	v_ashrrev_i32_e32 v33, 31, v32
	v_lshlrev_b64 v[32:33], 12, v[32:33]
	v_add_u32_e32 v36, 56, v36
	v_lshl_add_u64 v[32:33], v[16:17], 0, v[32:33]
	v_ashrrev_i32_e32 v37, 31, v36
	global_load_dwordx4 v[32:35], v[32:33], off nt
	v_lshlrev_b64 v[36:37], 12, v[36:37]
	v_lshl_add_u64 v[16:17], v[16:17], 0, v[36:37]
	global_load_dwordx4 v[36:39], v[16:17], off nt
	v_lshlrev_b32_e32 v16, 3, v18
	v_mul_lo_u32 v17, v19, s50
	v_readlane_b32 s16, v253, 35
	v_and_b32_e32 v16, 56, v16
	s_lshl_b32 s5, s5, 1
	v_add3_u32 v10, s16, v10, v17
	v_mul_u32_u24_e32 v17, 0x84, v16
	v_add_u32_e32 v43, 0x420, v10
	v_add_u32_e32 v44, 0x428, v10
	v_add_u32_e32 v45, 0x840, v10
	v_add_u32_e32 v46, 0x848, v10
	v_add_u32_e32 v47, 0xc60, v10
	v_add_u32_e32 v48, 0xc68, v10
	v_add_u32_e32 v49, 0x1080, v10
	v_add_u32_e32 v50, 0x1088, v10
	v_add_u32_e32 v51, 0x14a0, v10
	v_add_u32_e32 v52, 0x14a8, v10
	v_add_u32_e32 v53, 0x18c0, v10
	v_add_u32_e32 v54, 0x18c8, v10
	v_add_u32_e32 v55, 0x1ce0, v10
	v_add_u32_e32 v56, 0x1ce8, v10
	s_add_u32 s20, s38, s5
	s_addc_u32 s21, s39, 0
	v_readlane_b32 s60, v253, 40
	v_readlane_b32 s61, v253, 41
	s_waitcnt vmcnt(7)
	ds_write2_b32 v10, v2, v3 offset1:1
	ds_write2_b32 v10, v4, v5 offset0:2 offset1:3
	s_waitcnt vmcnt(6)
	ds_write2_b32 v43, v6, v7 offset1:1
	ds_write2_b32 v44, v8, v9 offset1:1
	s_waitcnt vmcnt(5)
	ds_write2_b32 v45, v12, v13 offset1:1
	ds_write2_b32 v46, v14, v15 offset1:1
	s_waitcnt vmcnt(4)
	ds_write2_b32 v47, v20, v21 offset1:1
	ds_write2_b32 v48, v22, v23 offset1:1
	s_waitcnt vmcnt(3)
	ds_write2_b32 v49, v24, v25 offset1:1
	ds_write2_b32 v50, v26, v27 offset1:1
	s_waitcnt vmcnt(2)
	ds_write2_b32 v51, v28, v29 offset1:1
	ds_write2_b32 v52, v30, v31 offset1:1
	s_waitcnt vmcnt(1)
	ds_write2_b32 v53, v32, v33 offset1:1
	ds_write2_b32 v54, v34, v35 offset1:1
	s_waitcnt vmcnt(0)
	ds_write2_b32 v55, v36, v37 offset1:1
	ds_write2_b32 v56, v38, v39 offset1:1
	v_lshlrev_b32_e32 v2, 2, v19
	s_waitcnt lgkmcnt(0)
	v_add3_u32 v30, s16, v17, v2
	v_lshlrev_b32_e32 v10, 1, v16
	ds_read2_b32 v[6:7], v30 offset0:33 offset1:41
	ds_read2_b32 v[8:9], v30 offset1:8
	ds_read2_b32 v[12:13], v30 offset0:66 offset1:74
	ds_read2_b32 v[14:15], v30 offset0:99 offset1:107
	ds_read2_b32 v[16:17], v30 offset0:132 offset1:140
	ds_read2_b32 v[20:21], v30 offset0:165 offset1:173
	ds_read2_b32 v[22:23], v30 offset0:198 offset1:206
	ds_read2_b32 v[24:25], v30 offset0:231 offset1:239
	v_add_u32_e32 v28, s4, v19
	v_ashrrev_i32_e32 v29, 31, v28
	v_lshl_add_u64 v[26:27], s[20:21], 0, v[10:11]
	v_lshlrev_b64 v[28:29], 11, v[28:29]
	s_waitcnt lgkmcnt(6)
	v_cvt_pk_bf16_f32 v2, v8, v6
	s_waitcnt lgkmcnt(4)
	v_cvt_pk_bf16_f32 v3, v12, v14
	s_waitcnt lgkmcnt(2)
	v_cvt_pk_bf16_f32 v4, v16, v20
	s_waitcnt lgkmcnt(0)
	v_cvt_pk_bf16_f32 v5, v22, v24
	v_lshl_add_u64 v[28:29], v[26:27], 0, v[28:29]
	v_add_u32_e32 v6, s4, v40
	global_store_dwordx4 v[28:29], v[2:5], off
	s_nop 1
	v_cvt_pk_bf16_f32 v2, v9, v7
	v_ashrrev_i32_e32 v7, 31, v6
	v_cvt_pk_bf16_f32 v3, v13, v15
	v_cvt_pk_bf16_f32 v4, v17, v21
	v_cvt_pk_bf16_f32 v5, v23, v25
	v_lshlrev_b64 v[6:7], 11, v[6:7]
	ds_read2_b32 v[8:9], v30 offset0:49 offset1:57
	ds_read2_b32 v[12:13], v30 offset0:16 offset1:24
	ds_read2_b32 v[14:15], v30 offset0:82 offset1:90
	ds_read2_b32 v[16:17], v30 offset0:115 offset1:123
	ds_read2_b32 v[20:21], v30 offset0:148 offset1:156
	ds_read2_b32 v[22:23], v30 offset0:181 offset1:189
	ds_read2_b32 v[24:25], v30 offset0:214 offset1:222
	ds_read2_b32 v[28:29], v30 offset0:247 offset1:255
	v_lshl_add_u64 v[6:7], v[26:27], 0, v[6:7]
	global_store_dwordx4 v[6:7], v[2:5], off
	v_add_u32_e32 v6, s4, v41
	v_ashrrev_i32_e32 v7, 31, v6
	v_lshlrev_b64 v[6:7], 11, v[6:7]
	s_waitcnt lgkmcnt(6)
	v_cvt_pk_bf16_f32 v2, v12, v8
	s_waitcnt lgkmcnt(4)
	v_cvt_pk_bf16_f32 v3, v14, v16
	s_waitcnt lgkmcnt(2)
	v_cvt_pk_bf16_f32 v4, v20, v22
	s_waitcnt lgkmcnt(0)
	v_cvt_pk_bf16_f32 v5, v24, v28
	v_lshl_add_u64 v[6:7], v[26:27], 0, v[6:7]
	global_store_dwordx4 v[6:7], v[2:5], off
	v_add_u32_e32 v6, s4, v42
	v_ashrrev_i32_e32 v7, 31, v6
	v_lshlrev_b64 v[6:7], 11, v[6:7]
	v_cvt_pk_bf16_f32 v2, v13, v9
	v_cvt_pk_bf16_f32 v3, v15, v17
	v_cvt_pk_bf16_f32 v4, v21, v23
	v_cvt_pk_bf16_f32 v5, v25, v29
	v_lshl_add_u64 v[6:7], v[26:27], 0, v[6:7]
	global_store_dwordx4 v[6:7], v[2:5], off
	s_waitcnt lgkmcnt(0)

.LBB0_98:
	s_load_dwordx16 s[72:87], s[0:1], 0x40
	s_lshl_b32 s20, s5, 6
	s_ashr_i32 s5, s4, 31
	v_lshlrev_b32_e32 v2, 2, v18
	s_lshl_b64 s[4:5], s[4:5], 2
	v_and_b32_e32 v20, 28, v2
	s_waitcnt lgkmcnt(0)
	s_add_u32 s4, s74, s4
	v_ashrrev_i32_e32 v19, 3, v18
	s_addc_u32 s5, s75, s5
	v_lshlrev_b32_e32 v10, 2, v20
	v_lshl_add_u64 v[12:13], s[4:5], 0, v[10:11]
	v_add_u32_e32 v14, s20, v19
	v_mad_i64_i32 v[2:3], s[4:5], v14, s51, v[12:13]
	global_load_dwordx4 v[2:5], v[2:3], off nt
	v_ashrrev_i32_e32 v15, 31, v14
	v_cndmask_b32_e64 v6, 0, 1, s[14:15]
	v_cmp_ne_u32_e64 s[4:5], 1, v6
	s_andn2_b64 vcc, exec, s[14:15]
	v_lshl_add_u64 v[16:17], v[14:15], 2, s[72:73]
	s_cbranch_vccnz .LBB0_100
	global_load_dword v6, v[16:17], off
	s_waitcnt vmcnt(0)
	v_pk_mul_f32 v[4:5], v[4:5], v[6:7] op_sel_hi:[1,0]
	v_pk_mul_f32 v[2:3], v[2:3], v[6:7] op_sel_hi:[1,0]
.LBB0_100:
	v_add_u32_e32 v15, 8, v19
	v_add_u32_e32 v6, s20, v15
	v_mad_i64_i32 v[6:7], s[54:55], v6, s51, v[12:13]
	global_load_dwordx4 v[6:9], v[6:7], off nt
	v_readlane_b32 s21, v253, 35
	v_readlane_b32 s60, v253, 40
	s_and_b64 vcc, exec, s[4:5]
	v_lshl_add_u32 v10, v20, 2, s21
	v_mul_lo_u32 v20, v19, s50
	v_add_u32_e32 v10, v10, v20
	v_readlane_b32 s61, v253, 41
	s_waitcnt vmcnt(1)
	ds_write2_b32 v10, v2, v3 offset1:1
	ds_write2_b32 v10, v4, v5 offset0:2 offset1:3
	s_cbranch_vccnz .LBB0_102
	global_load_dword v2, v[16:17], off offset:32
	s_waitcnt vmcnt(0)
	v_pk_mul_f32 v[8:9], v[8:9], v[2:3] op_sel_hi:[1,0]
	v_pk_mul_f32 v[6:7], v[6:7], v[2:3] op_sel_hi:[1,0]
.LBB0_102:
	v_add_u32_e32 v20, 16, v19
	v_add_u32_e32 v2, s20, v20
	v_mad_i64_i32 v[2:3], s[54:55], v2, s51, v[12:13]
	global_load_dwordx4 v[2:5], v[2:3], off nt
	v_add_u32_e32 v21, 0x420, v10
	s_waitcnt vmcnt(1)
	ds_write2_b32 v21, v6, v7 offset1:1
	v_add_u32_e32 v6, 0x428, v10
	s_and_b64 vcc, exec, s[4:5]
	ds_write2_b32 v6, v8, v9 offset1:1
	s_cbranch_vccnz .LBB0_104
	global_load_dword v6, v[16:17], off offset:64
	s_waitcnt vmcnt(0)
	v_pk_mul_f32 v[4:5], v[4:5], v[6:7] op_sel_hi:[1,0]
	v_pk_mul_f32 v[2:3], v[2:3], v[6:7] op_sel_hi:[1,0]
.LBB0_104:
	v_add_u32_e32 v21, 24, v19
	v_add_u32_e32 v6, s20, v21
	v_mad_i64_i32 v[6:7], s[54:55], v6, s51, v[12:13]
	global_load_dwordx4 v[6:9], v[6:7], off nt
	v_add_u32_e32 v22, 0x840, v10
	s_waitcnt vmcnt(1)
	ds_write2_b32 v22, v2, v3 offset1:1
	v_add_u32_e32 v2, 0x848, v10
	s_and_b64 vcc, exec, s[4:5]
	ds_write2_b32 v2, v4, v5 offset1:1
	s_cbranch_vccnz .LBB0_106
	global_load_dword v2, v[16:17], off offset:96
	s_waitcnt vmcnt(0)
	v_pk_mul_f32 v[8:9], v[8:9], v[2:3] op_sel_hi:[1,0]
	v_pk_mul_f32 v[6:7], v[6:7], v[2:3] op_sel_hi:[1,0]
.LBB0_106:
	v_add_u32_e32 v2, 32, v14
	v_mad_i64_i32 v[2:3], s[54:55], v2, s51, v[12:13]
	global_load_dwordx4 v[2:5], v[2:3], off nt
	v_add_u32_e32 v22, 0xc60, v10
	s_waitcnt vmcnt(1)
	ds_write2_b32 v22, v6, v7 offset1:1
	v_add_u32_e32 v6, 0xc68, v10
	s_and_b64 vcc, exec, s[4:5]
	ds_write2_b32 v6, v8, v9 offset1:1
	s_cbranch_vccnz .LBB0_108
	global_load_dword v6, v[16:17], off offset:128
	s_waitcnt vmcnt(0)
	v_pk_mul_f32 v[4:5], v[4:5], v[6:7] op_sel_hi:[1,0]
	v_pk_mul_f32 v[2:3], v[2:3], v[6:7] op_sel_hi:[1,0]
.LBB0_108:
	v_add_u32_e32 v6, 40, v14
	v_mad_i64_i32 v[6:7], s[54:55], v6, s51, v[12:13]
	global_load_dwordx4 v[6:9], v[6:7], off nt
	v_add_u32_e32 v22, 0x1080, v10
	s_waitcnt vmcnt(1)
	ds_write2_b32 v22, v2, v3 offset1:1
	v_add_u32_e32 v2, 0x1088, v10
	s_and_b64 vcc, exec, s[4:5]
	ds_write2_b32 v2, v4, v5 offset1:1
	s_cbranch_vccnz .LBB0_110
	global_load_dword v2, v[16:17], off offset:160
	s_waitcnt vmcnt(0)
	v_pk_mul_f32 v[8:9], v[8:9], v[2:3] op_sel_hi:[1,0]
	v_pk_mul_f32 v[6:7], v[6:7], v[2:3] op_sel_hi:[1,0]
.LBB0_110:
	v_add_u32_e32 v2, 48, v14
	v_mad_i64_i32 v[2:3], s[54:55], v2, s51, v[12:13]
	global_load_dwordx4 v[2:5], v[2:3], off nt
	v_add_u32_e32 v22, 0x14a0, v10
	s_waitcnt vmcnt(1)
	ds_write2_b32 v22, v6, v7 offset1:1
	v_add_u32_e32 v6, 0x14a8, v10
	s_and_b64 vcc, exec, s[4:5]
	ds_write2_b32 v6, v8, v9 offset1:1
	s_cbranch_vccnz .LBB0_112
	global_load_dword v6, v[16:17], off offset:192
	s_waitcnt vmcnt(0)
	v_pk_mul_f32 v[4:5], v[4:5], v[6:7] op_sel_hi:[1,0]
	v_pk_mul_f32 v[2:3], v[2:3], v[6:7] op_sel_hi:[1,0]
.LBB0_112:
	v_add_u32_e32 v6, 56, v14
	v_mad_i64_i32 v[6:7], s[54:55], v6, s51, v[12:13]
	global_load_dwordx4 v[6:9], v[6:7], off nt
	v_add_u32_e32 v12, 0x18c0, v10
	s_waitcnt vmcnt(1)
	ds_write2_b32 v12, v2, v3 offset1:1
	v_add_u32_e32 v2, 0x18c8, v10
	s_and_b64 vcc, exec, s[4:5]
	ds_write2_b32 v2, v4, v5 offset1:1
	s_cbranch_vccnz .LBB0_7
	global_load_dword v2, v[16:17], off offset:224
	s_waitcnt vmcnt(0)
	v_pk_mul_f32 v[8:9], v[8:9], v[2:3] op_sel_hi:[1,0]
	v_pk_mul_f32 v[6:7], v[6:7], v[2:3] op_sel_hi:[1,0]
	s_branch .LBB0_7

.LBB0_139:
	s_lshl_b64 s[26:27], s[26:27], 12
	s_add_u32 s24, s24, s26
	s_addc_u32 s25, s25, s27
	s_add_i32 s10, s14, 0xffffbc00
	s_ashr_i32 s15, s14, 31
	s_cmpk_lt_i32 s14, 0x4400
	global_load_dwordx4 v[14:17], v31, s[24:25] nt
	global_load_dwordx4 v[10:13], v31, s[24:25] offset:1024 nt
	global_load_dwordx4 v[2:5], v31, s[24:25] offset:3072 nt
	global_load_dwordx4 v[6:9], v31, s[24:25] offset:2048 nt
	s_cselect_b64 s[24:25], -1, 0
	s_and_b64 s[26:27], s[24:25], exec
	s_cselect_b32 s27, s15, 0
	s_cselect_b32 s26, s14, s10
	s_cselect_b32 s10, s37, s64
	s_cselect_b32 s30, s36, s81
	s_lshl_b64 s[26:27], s[26:27], 11
	s_add_u32 s26, s30, s26
	s_addc_u32 s27, s10, s27
	s_lshl_b64 s[28:29], s[28:29], 12
	s_add_u32 s4, s4, s28
	s_addc_u32 s5, s5, s29
	global_load_dwordx4 v[34:37], v31, s[4:5] nt
	global_load_dwordx4 v[38:41], v31, s[4:5] offset:1024 nt
	global_load_dwordx4 v[42:45], v31, s[4:5] offset:3072 nt
	global_load_dwordx4 v[46:49], v31, s[4:5] offset:2048 nt
	s_cmpk_gt_i32 s14, 0x43ff
	s_waitcnt vmcnt(7)
	v_pk_mul_f32 v[22:23], v[16:17], v[16:17]
	v_pk_mul_f32 v[24:25], v[14:15], v[14:15]
	s_waitcnt vmcnt(6)
	v_pk_mul_f32 v[50:51], v[12:13], v[12:13]
	v_pk_mul_f32 v[52:53], v[10:11], v[10:11]
	v_pk_mov_b32 v[58:59], v[24:25], v[22:23] op_sel:[1,0]
	v_mov_b32_e32 v25, v23
	v_pk_mov_b32 v[22:23], v[52:53], v[50:51] op_sel:[1,0]
	v_mov_b32_e32 v53, v51
	s_waitcnt vmcnt(5)
	v_mul_f32_e32 v57, v3, v3
	s_waitcnt vmcnt(4)
	v_mul_f32_e32 v54, v7, v7
	v_mul_f32_e32 v56, v9, v9
	v_pk_add_f32 v[24:25], v[58:59], v[24:25]
	v_pk_add_f32 v[22:23], v[22:23], v[52:53]
	v_mul_f32_e32 v33, v2, v2
	v_mul_f32_e32 v60, v4, v4
	v_mul_f32_e32 v61, v5, v5
	v_pk_fma_f32 v[50:51], v[6:7], v[6:7], v[54:55] op_sel_hi:[1,1,0]
	v_pk_fma_f32 v[54:55], v[8:9], v[8:9], v[56:57] op_sel_hi:[1,1,0]
	v_pk_add_f32 v[24:25], v[24:25], v[24:25] op_sel:[0,1] op_sel_hi:[1,0]
	v_pk_add_f32 v[22:23], v[22:23], v[22:23] op_sel:[0,1] op_sel_hi:[1,0]
	v_mov_b32_e32 v51, v60
	v_mov_b32_e32 v55, v61
	v_mov_b32_e32 v25, v33
	v_mov_b32_e32 v23, v57
	v_pk_add_f32 v[50:51], v[50:51], v[54:55]
	v_pk_add_f32 v[22:23], v[24:25], v[22:23]
	s_waitcnt vmcnt(3)
	v_pk_mul_f32 v[52:53], v[34:35], v[34:35]
	v_pk_add_f32 v[22:23], v[22:23], v[50:51]
	v_pk_mul_f32 v[50:51], v[36:37], v[36:37]
	s_waitcnt vmcnt(2)
	v_pk_mul_f32 v[54:55], v[40:41], v[40:41]
	v_pk_mul_f32 v[56:57], v[38:39], v[38:39]
	v_pk_mov_b32 v[60:61], v[52:53], v[50:51] op_sel:[1,0]
	v_mov_b32_e32 v53, v51
	v_pk_mov_b32 v[50:51], v[56:57], v[54:55] op_sel:[1,0]
	v_mov_b32_e32 v57, v55
	v_mov_b32_e32 v24, v22
	s_waitcnt vmcnt(0)
	v_mul_f32_e32 v22, v47, v47
	v_mul_f32_e32 v58, v49, v49
	v_pk_add_f32 v[52:53], v[60:61], v[52:53]
	v_pk_add_f32 v[50:51], v[50:51], v[56:57]
	v_mul_f32_e32 v25, v42, v42
	v_mul_f32_e32 v33, v43, v43
	v_mul_f32_e32 v62, v44, v44
	v_mul_f32_e32 v63, v45, v45
	v_pk_fma_f32 v[54:55], v[46:47], v[46:47], v[22:23] op_sel_hi:[1,1,0]
	v_pk_fma_f32 v[58:59], v[48:49], v[48:49], v[58:59] op_sel_hi:[1,1,0]
	v_pk_add_f32 v[52:53], v[52:53], v[52:53] op_sel:[0,1] op_sel_hi:[1,0]
	v_pk_add_f32 v[50:51], v[50:51], v[50:51] op_sel:[0,1] op_sel_hi:[1,0]
	v_mov_b32_e32 v55, v62
	v_mov_b32_e32 v59, v63
	v_mov_b32_e32 v53, v25
	v_mov_b32_e32 v51, v33
	v_pk_add_f32 v[54:55], v[54:55], v[58:59]
	v_pk_add_f32 v[50:51], v[52:53], v[50:51]
	s_nop 0
	v_pk_add_f32 v[50:51], v[50:51], v[54:55]
	s_nop 0
	v_mov_b32_e32 v25, v50
	v_mov_b32_e32 v50, v23
	v_pk_add_f32 v[22:23], v[24:25], v[50:51]
	ds_bpermute_b32 v25, v1, v23
	ds_bpermute_b32 v24, v1, v22
	s_waitcnt lgkmcnt(0)
	v_pk_add_f32 v[22:23], v[22:23], v[24:25]
	ds_bpermute_b32 v25, v26, v23
	ds_bpermute_b32 v24, v26, v22
	s_waitcnt lgkmcnt(0)
	v_pk_add_f32 v[22:23], v[22:23], v[24:25]
	ds_bpermute_b32 v25, v27, v23
	ds_bpermute_b32 v24, v27, v22
	s_waitcnt lgkmcnt(0)
	v_pk_add_f32 v[22:23], v[22:23], v[24:25]
	ds_bpermute_b32 v25, v28, v23
	ds_bpermute_b32 v24, v28, v22
	s_waitcnt lgkmcnt(0)
	v_pk_add_f32 v[22:23], v[22:23], v[24:25]
	ds_bpermute_b32 v25, v29, v23
	ds_bpermute_b32 v24, v29, v22
	s_waitcnt lgkmcnt(0)
	v_pk_add_f32 v[22:23], v[22:23], v[24:25]
	ds_bpermute_b32 v25, v30, v23
	ds_bpermute_b32 v24, v30, v22
	s_waitcnt lgkmcnt(0)
	v_pk_add_f32 v[22:23], v[22:23], v[24:25]
	s_nop 0
	v_pk_fma_f32 v[24:25], v[22:23], s[12:13], v[20:21] op_sel_hi:[1,0,0]
	s_nop 0
	v_mul_f32_e32 v33, 0x4b800000, v25
	v_cmp_gt_f32_e32 vcc, s3, v25
	v_cmp_gt_f32_e64 s[4:5], s3, v24
	s_nop 0
	v_cndmask_b32_e32 v25, v25, v33, vcc
	v_rsq_f32_e32 v25, v25
	s_nop 0
	v_mul_f32_e32 v33, 0x45800000, v25
	v_cndmask_b32_e32 v25, v25, v33, vcc
	s_cselect_b64 vcc, -1, 0
	v_cndmask_b32_e32 v50, 1.0, v25, vcc
	v_pk_mul_f32 v[34:35], v[34:35], v[50:51] op_sel_hi:[1,0]
	v_pk_mul_f32 v[36:37], v[36:37], v[50:51] op_sel_hi:[1,0]
	v_pk_mul_f32 v[38:39], v[38:39], v[50:51] op_sel_hi:[1,0]
	v_pk_mul_f32 v[40:41], v[40:41], v[50:51] op_sel_hi:[1,0]
	v_pk_mul_f32 v[46:47], v[46:47], v[50:51] op_sel_hi:[1,0]
	v_pk_mul_f32 v[48:49], v[48:49], v[50:51] op_sel_hi:[1,0]
	v_pk_mul_f32 v[42:43], v[42:43], v[50:51] op_sel_hi:[1,0]
	v_pk_mul_f32 v[44:45], v[44:45], v[50:51] op_sel_hi:[1,0]
	v_cvt_pk_bf16_f32 v34, v34, v35
	v_cvt_pk_bf16_f32 v35, v36, v37
	v_cvt_pk_bf16_f32 v36, v38, v39
	v_cvt_pk_bf16_f32 v37, v40, v41
	v_cvt_pk_bf16_f32 v38, v46, v47
	v_cvt_pk_bf16_f32 v39, v48, v49
	v_cvt_pk_bf16_f32 v40, v42, v43
	v_cvt_pk_bf16_f32 v41, v44, v45
	global_store_dwordx2 v32, v[34:35], s[26:27]
	global_store_dwordx2 v32, v[36:37], s[26:27] offset:512
	global_store_dwordx2 v32, v[38:39], s[26:27] offset:1024
	global_store_dwordx2 v32, v[40:41], s[26:27] offset:1536
	s_and_b64 s[26:27], s[24:25], s[0:1]
	s_and_saveexec_b64 s[24:25], s[26:27]
	s_cbranch_execnz .LBB0_141
	s_or_b64 exec, exec, s[24:25]
	s_andn2_b64 vcc, exec, s[18:19]
	s_cbranch_vccnz .LBB0_118
	s_branch .LBB0_142
